# v22 + QKV epilogue: next row-group rope-table loads hoisted above the current group's stores (landing regs + moves)
# speedup vs baseline: 1.0068x; 1.0068x over previous
; DI unsigned pk2(float lo, float hi) { f32x2 v = {lo, hi}; bf16x2_t b = __builtin_convertvector(v, bf16x2_t); return __builtin_bit_cast(unsigned, b); }
; template <int MODE> DI void epilogue(const Epi& E, f32x4 (&acc)[2][2][4][2], const Unit& u, int wr, int wc, int fr, int fq) {
;     ...
;                 const int row = row0 + ai * HALF + m * 16; const int pos = pos_of_row(row);
;                 f32x4 c0 = {1.f, 1.f, 1.f, 1.f}, c1 = c0, s0 = {0.f, 0.f, 0.f, 0.f}, s1 = s0;
;                 if (rp) { const f32x4* rt = (const f32x4*)(E.rope + (size_t)pos * 16); c0 = rt[0]; c1 = rt[1]; s0 = rt[2]; s1 = rt[3]; }
;                 const int pl0 = ((colt / 1536) * 3 + typ) * 8;
; #pragma unroll
;                 for (int bj = 0; bj < 2; ++bj) {
;                     const int hh_ = (((colt & 511) + wc * 64) >> 6);
;                     bf16_t* rowp = E.O + ((size_t)(pl0 + hh_) * T + row) * 64 + bj * 32 + 8 * fq;
;                     f32x4 v0 = acc[ai][bj][m][0], v1 = acc[ai][bj][m][1];
;                     if (rp && bj == 0) {
;                         f32x4 p0, p1;
; #pragma unroll
;                         for (int e = 0; e < 4; ++e) { p0[e] = __shfl_xor(v0[e], 16); p1[e] = __shfl_xor(v1[e], 16); }
;                         if (fq == 0) { v0 = v0 * c0 - p0 * s0; v1 = v1 * c1 - p1 * s1; }
;                         else if (fq == 1) { v0 = v0 * c0 + p0 * s0; v1 = v1 * c1 + p1 * s1; }
;                     }
;                     u32x4 w; w.x = pk2(v0[0], v0[1]); w.y = pk2(v0[2], v0[3]); w.z = pk2(v1[0], v1[1]); w.w = pk2(v1[2], v1[3]);
;                     __builtin_nontemporal_store(w, (u32x4*)rowp);
.LBB0_219:
	s_mul_hi_i32 s20, s20, 0x2aaaaaab
	s_lshr_b32 s21, s20, 31
	s_add_i32 s20, s20, s21
	s_mul_i32 s20, s20, 3
	s_add_i32 s15, s15, s20
	s_lshr_b32 s3, s3, 6
	s_lshl_b32 s15, s15, 3
	s_and_b32 s3, s3, 4
	s_or_b32 s3, s15, s3
	s_or_b32 s3, s3, s37
	v_ashrrev_i32_e32 v179, 31, v178
	s_waitcnt vmcnt(0)
	v_mad_i64_i32 v[128:129], s[20:21], s3, v195, v[178:179]
	v_lshlrev_b64 v[128:129], 7, v[128:129]
	v_lshl_add_u64 v[128:129], v[168:169], 0, v[128:129]
	v_cvt_pk_bf16_f32 v124, v124, v125
	v_cvt_pk_bf16_f32 v125, v126, v127
	v_cvt_pk_bf16_f32 v126, v120, v121
	v_cvt_pk_bf16_f32 v127, v122, v123
	v_cvt_pk_bf16_f32 v116, v116, v117
	v_cvt_pk_bf16_f32 v117, v118, v119
	v_cvt_pk_bf16_f32 v118, v112, v113
	v_cvt_pk_bf16_f32 v119, v114, v115
	v_or_b32_e32 v220, 16, v178
	s_and_b64 vcc, exec, s[4:5]
	s_cbranch_vccnz .Lrope_pf_skip_1
	v_cmp_gt_i32_e32 vcc, s36, v220
	s_nop 1
	v_cndmask_b32_e32 v221, v196, v197, vcc
	v_and_b32_e32 v221, v221, v220
	v_lshlrev_b32_e32 v221, 6, v221
	global_load_dwordx4 v[204:207], v221, s[6:7] offset:32
	global_load_dwordx4 v[208:211], v221, s[6:7] offset:48
	global_load_dwordx4 v[212:215], v221, s[6:7] offset:16
	global_load_dwordx4 v[216:219], v221, s[6:7]
.Lrope_pf_skip_1:
	s_and_b64 vcc, exec, s[4:5]
	v_or_b32_e32 v144, 16, v178
	global_store_dwordx4 v[128:129], v[124:127], off nt
	global_store_dwordx4 v[128:129], v[116:119], off offset:64 nt
	s_cbranch_vccnz .LBB0_221
	v_cmp_gt_i32_e32 vcc, s36, v144
	s_nop 1
	v_cndmask_b32_e32 v112, v196, v197, vcc
	v_and_b32_e32 v112, v112, v144
	v_lshlrev_b32_e32 v124, 6, v112
	s_waitcnt vmcnt(2)
	v_mov_b32_e32 v120, v204
	v_mov_b32_e32 v121, v205
	v_mov_b32_e32 v122, v206
	v_mov_b32_e32 v123, v207
	v_mov_b32_e32 v116, v208
	v_mov_b32_e32 v117, v209
	v_mov_b32_e32 v118, v210
	v_mov_b32_e32 v119, v211
	v_mov_b32_e32 v112, v212
	v_mov_b32_e32 v113, v213
	v_mov_b32_e32 v114, v214
	v_mov_b32_e32 v115, v215
	v_mov_b32_e32 v124, v216
	v_mov_b32_e32 v125, v217
	v_mov_b32_e32 v126, v218
	v_mov_b32_e32 v127, v219
	s_and_b64 vcc, exec, s[4:5]
	s_cbranch_vccz .LBB0_222
	s_branch .LBB0_229

; template <int MODE> DI void epilogue(const Epi& E, f32x4 (&acc)[2][2][4][2], const Unit& u, int wr, int wc, int fr, int fq) {
;     ...
;                     if (rp && bj == 0) {
;                         f32x4 p0, p1;
; #pragma unroll
;                         for (int e = 0; e < 4; ++e) { p0[e] = __shfl_xor(v0[e], 16); p1[e] = __shfl_xor(v1[e], 16); }
;                         if (fq == 0) { v0 = v0 * c0 - p0 * s0; v1 = v1 * c1 - p1 * s1; }
;                         else if (fq == 1) { v0 = v0 * c0 + p0 * s0; v1 = v1 * c1 + p1 * s1; }
.LBB0_222:
	v_and_b32_e32 v129, 64, v194
	v_xor_b32_e32 v128, 16, v194
	v_add_u32_e32 v129, 64, v129
	v_cmp_lt_i32_e32 vcc, v128, v129
	s_nop 1
	v_cndmask_b32_e32 v128, v194, v128, vcc
	v_lshlrev_b32_e32 v128, 2, v128
	ds_bpermute_b32 v140, v128, v108
	ds_bpermute_b32 v132, v128, v104
	ds_bpermute_b32 v141, v128, v109
	ds_bpermute_b32 v133, v128, v105
	s_waitcnt lgkmcnt(10)
	ds_bpermute_b32 v148, v128, v110
	ds_bpermute_b32 v146, v128, v106
	s_waitcnt lgkmcnt(10)
	ds_bpermute_b32 v149, v128, v111
	ds_bpermute_b32 v147, v128, v107
	v_cmp_lt_i32_e32 vcc, 0, v184
	s_and_saveexec_b64 s[20:21], vcc
	s_xor_b64 s[20:21], exec, s[20:21]
	s_cbranch_execz .LBB0_226
	v_mov_b64_e32 v[138:139], v[106:107]
	v_mov_b64_e32 v[130:131], v[110:111]
	v_cmp_eq_u32_e32 vcc, 1, v184
	v_mov_b64_e32 v[136:137], v[104:105]
	v_mov_b64_e32 v[128:129], v[108:109]
	s_and_saveexec_b64 s[22:23], vcc
	s_cbranch_execz .LBB0_225
	s_waitcnt vmcnt(3) lgkmcnt(1)
	v_pk_mul_f32 v[122:123], v[122:123], v[148:149]
	v_pk_mul_f32 v[120:121], v[120:121], v[140:141]
	s_waitcnt vmcnt(2) lgkmcnt(0)
	v_pk_mul_f32 v[118:119], v[118:119], v[146:147]
	v_pk_mul_f32 v[116:117], v[116:117], v[132:133]
	s_waitcnt vmcnt(2)
	v_pk_fma_f32 v[130:131], v[110:111], v[126:127], v[122:123]
	v_pk_fma_f32 v[128:129], v[108:109], v[124:125], v[120:121]
	v_pk_fma_f32 v[138:139], v[106:107], v[114:115], v[118:119]
	v_pk_fma_f32 v[136:137], v[104:105], v[112:113], v[116:117]

; template <int MODE> DI void epilogue(const Epi& E, f32x4 (&acc)[2][2][4][2], const Unit& u, int wr, int wc, int fr, int fq) {
;     ...
;                     if (rp && bj == 0) {
;                         f32x4 p0, p1;
; #pragma unroll
;                         for (int e = 0; e < 4; ++e) { p0[e] = __shfl_xor(v0[e], 16); p1[e] = __shfl_xor(v1[e], 16); }
;                         if (fq == 0) { v0 = v0 * c0 - p0 * s0; v1 = v1 * c1 - p1 * s1; }
;                         else if (fq == 1) { v0 = v0 * c0 + p0 * s0; v1 = v1 * c1 + p1 * s1; }
.LBB0_226:
	s_andn2_saveexec_b64 s[20:21], s[20:21]
	s_cbranch_execz .LBB0_228
	s_waitcnt vmcnt(3) lgkmcnt(1)
	v_pk_mul_f32 v[122:123], v[122:123], v[148:149]
	v_pk_mul_f32 v[120:121], v[120:121], v[140:141]
	s_waitcnt vmcnt(2)
	v_pk_fma_f32 v[130:131], v[110:111], v[126:127], v[122:123] neg_lo:[0,0,1] neg_hi:[0,0,1]
	v_pk_fma_f32 v[128:129], v[108:109], v[124:125], v[120:121] neg_lo:[0,0,1] neg_hi:[0,0,1]
	s_waitcnt lgkmcnt(0)
	v_pk_mul_f32 v[108:109], v[118:119], v[146:147]
	v_pk_mul_f32 v[110:111], v[116:117], v[132:133]
	v_pk_fma_f32 v[138:139], v[106:107], v[114:115], v[108:109] neg_lo:[0,0,1] neg_hi:[0,0,1]
	v_pk_fma_f32 v[136:137], v[104:105], v[112:113], v[110:111] neg_lo:[0,0,1] neg_hi:[0,0,1]

; DI unsigned pk2(float lo, float hi) { f32x2 v = {lo, hi}; bf16x2_t b = __builtin_convertvector(v, bf16x2_t); return __builtin_bit_cast(unsigned, b); }
; template <int MODE> DI void epilogue(const Epi& E, f32x4 (&acc)[2][2][4][2], const Unit& u, int wr, int wc, int fr, int fq) {
;     ...
;                 const int row = row0 + ai * HALF + m * 16; const int pos = pos_of_row(row);
;                 f32x4 c0 = {1.f, 1.f, 1.f, 1.f}, c1 = c0, s0 = {0.f, 0.f, 0.f, 0.f}, s1 = s0;
;                 if (rp) { const f32x4* rt = (const f32x4*)(E.rope + (size_t)pos * 16); c0 = rt[0]; c1 = rt[1]; s0 = rt[2]; s1 = rt[3]; }
;                 const int pl0 = ((colt / 1536) * 3 + typ) * 8;
; #pragma unroll
;                 for (int bj = 0; bj < 2; ++bj) {
;                     const int hh_ = (((colt & 511) + wc * 64) >> 6);
;                     bf16_t* rowp = E.O + ((size_t)(pl0 + hh_) * T + row) * 64 + bj * 32 + 8 * fq;
;                     f32x4 v0 = acc[ai][bj][m][0], v1 = acc[ai][bj][m][1];
;                     if (rp && bj == 0) {
;                         f32x4 p0, p1;
; #pragma unroll
;                         for (int e = 0; e < 4; ++e) { p0[e] = __shfl_xor(v0[e], 16); p1[e] = __shfl_xor(v1[e], 16); }
;                         if (fq == 0) { v0 = v0 * c0 - p0 * s0; v1 = v1 * c1 - p1 * s1; }
;                         else if (fq == 1) { v0 = v0 * c0 + p0 * s0; v1 = v1 * c1 + p1 * s1; }
;                     }
;                     u32x4 w; w.x = pk2(v0[0], v0[1]); w.y = pk2(v0[2], v0[3]); w.z = pk2(v1[0], v1[1]); w.w = pk2(v1[2], v1[3]);
;                     __builtin_nontemporal_store(w, (u32x4*)rowp);
.LBB0_229:
	s_mul_hi_i32 s21, s3, 0x18000
	s_mul_i32 s20, s3, 0x18000
	v_ashrrev_i32_e32 v145, 31, v144
	s_waitcnt vmcnt(2)
	v_lshl_add_u64 v[112:113], s[20:21], 0, v[144:145]
	v_lshlrev_b64 v[112:113], 7, v[112:113]
	v_lshl_add_u64 v[112:113], v[168:169], 0, v[112:113]
	v_cvt_pk_bf16_f32 v108, v108, v109
	v_cvt_pk_bf16_f32 v109, v110, v111
	v_cvt_pk_bf16_f32 v110, v104, v105
	v_cvt_pk_bf16_f32 v111, v106, v107
	v_cvt_pk_bf16_f32 v100, v100, v101
	v_cvt_pk_bf16_f32 v101, v102, v103
	v_cvt_pk_bf16_f32 v102, v96, v97
	v_cvt_pk_bf16_f32 v103, v98, v99
	v_or_b32_e32 v220, 32, v178
	s_and_b64 vcc, exec, s[4:5]
	s_cbranch_vccnz .Lrope_pf_skip_2
	v_cmp_gt_i32_e32 vcc, s36, v220
	s_nop 1
	v_cndmask_b32_e32 v221, v198, v199, vcc
	v_and_b32_e32 v221, v221, v220
	v_lshlrev_b32_e32 v221, 6, v221
	global_load_dwordx4 v[204:207], v221, s[6:7] offset:32
	global_load_dwordx4 v[208:211], v221, s[6:7] offset:48
	global_load_dwordx4 v[212:215], v221, s[6:7] offset:16
	global_load_dwordx4 v[216:219], v221, s[6:7]
.Lrope_pf_skip_2:
	s_and_b64 vcc, exec, s[4:5]
	v_or_b32_e32 v128, 32, v178
	global_store_dwordx4 v[112:113], v[108:111], off nt
	global_store_dwordx4 v[112:113], v[100:103], off offset:64 nt
	s_cbranch_vccnz .LBB0_231
	v_cmp_gt_i32_e32 vcc, s36, v128
	s_nop 1
	v_cndmask_b32_e32 v96, v198, v199, vcc
	v_and_b32_e32 v96, v96, v128
	v_lshlrev_b32_e32 v108, 6, v96
	s_waitcnt vmcnt(2)
	v_mov_b32_e32 v104, v204
	v_mov_b32_e32 v105, v205
	v_mov_b32_e32 v106, v206
	v_mov_b32_e32 v107, v207
	v_mov_b32_e32 v100, v208
	v_mov_b32_e32 v101, v209
	v_mov_b32_e32 v102, v210
	v_mov_b32_e32 v103, v211
	v_mov_b32_e32 v96, v212
	v_mov_b32_e32 v97, v213
	v_mov_b32_e32 v98, v214
	v_mov_b32_e32 v99, v215
	v_mov_b32_e32 v108, v216
	v_mov_b32_e32 v109, v217
	v_mov_b32_e32 v110, v218
	v_mov_b32_e32 v111, v219
	s_and_b64 vcc, exec, s[4:5]
	s_cbranch_vccz .LBB0_232
	s_branch .LBB0_239

; template <int MODE> DI void epilogue(const Epi& E, f32x4 (&acc)[2][2][4][2], const Unit& u, int wr, int wc, int fr, int fq) {
;     ...
;                     if (rp && bj == 0) {
;                         f32x4 p0, p1;
; #pragma unroll
;                         for (int e = 0; e < 4; ++e) { p0[e] = __shfl_xor(v0[e], 16); p1[e] = __shfl_xor(v1[e], 16); }
;                         if (fq == 0) { v0 = v0 * c0 - p0 * s0; v1 = v1 * c1 - p1 * s1; }
;                         else if (fq == 1) { v0 = v0 * c0 + p0 * s0; v1 = v1 * c1 + p1 * s1; }
.LBB0_232:
	v_and_b32_e32 v113, 64, v194
	v_xor_b32_e32 v112, 16, v194
	v_add_u32_e32 v113, 64, v113
	v_cmp_lt_i32_e32 vcc, v112, v113
	s_nop 1
	v_cndmask_b32_e32 v112, v194, v112, vcc
	v_lshlrev_b32_e32 v112, 2, v112
	s_waitcnt vmcnt(2)
	ds_bpermute_b32 v124, v112, v92
	ds_bpermute_b32 v116, v112, v88
	ds_bpermute_b32 v125, v112, v93
	ds_bpermute_b32 v117, v112, v89
	s_waitcnt lgkmcnt(10)
	ds_bpermute_b32 v132, v112, v94
	ds_bpermute_b32 v130, v112, v90
	s_waitcnt lgkmcnt(10)
	ds_bpermute_b32 v133, v112, v95
	ds_bpermute_b32 v131, v112, v91
	v_cmp_lt_i32_e32 vcc, 0, v184
	s_and_saveexec_b64 s[22:23], vcc
	s_xor_b64 s[22:23], exec, s[22:23]
	s_cbranch_execz .LBB0_236
	v_mov_b64_e32 v[122:123], v[90:91]
	v_mov_b64_e32 v[114:115], v[94:95]
	v_cmp_eq_u32_e32 vcc, 1, v184
	v_mov_b64_e32 v[120:121], v[88:89]
	v_mov_b64_e32 v[112:113], v[92:93]
	s_and_saveexec_b64 s[24:25], vcc
	s_cbranch_execz .LBB0_235
	s_waitcnt lgkmcnt(1)
	v_pk_mul_f32 v[106:107], v[106:107], v[132:133]
	v_pk_mul_f32 v[104:105], v[104:105], v[124:125]
	s_waitcnt lgkmcnt(0)
	v_pk_mul_f32 v[102:103], v[102:103], v[130:131]
	v_pk_mul_f32 v[100:101], v[100:101], v[116:117]
	s_waitcnt vmcnt(2)
	v_pk_fma_f32 v[114:115], v[94:95], v[110:111], v[106:107]
	v_pk_fma_f32 v[112:113], v[92:93], v[108:109], v[104:105]
	v_pk_fma_f32 v[122:123], v[90:91], v[98:99], v[102:103]
	v_pk_fma_f32 v[120:121], v[88:89], v[96:97], v[100:101]

; template <int MODE> DI void epilogue(const Epi& E, f32x4 (&acc)[2][2][4][2], const Unit& u, int wr, int wc, int fr, int fq) {
;     ...
;                     if (rp && bj == 0) {
;                         f32x4 p0, p1;
; #pragma unroll
;                         for (int e = 0; e < 4; ++e) { p0[e] = __shfl_xor(v0[e], 16); p1[e] = __shfl_xor(v1[e], 16); }
;                         if (fq == 0) { v0 = v0 * c0 - p0 * s0; v1 = v1 * c1 - p1 * s1; }
;                         else if (fq == 1) { v0 = v0 * c0 + p0 * s0; v1 = v1 * c1 + p1 * s1; }
.LBB0_236:
	s_andn2_saveexec_b64 s[22:23], s[22:23]
	s_cbranch_execz .LBB0_238
	s_waitcnt lgkmcnt(1)
	v_pk_mul_f32 v[106:107], v[106:107], v[132:133]
	v_pk_mul_f32 v[104:105], v[104:105], v[124:125]
	s_waitcnt vmcnt(2)
	v_pk_fma_f32 v[114:115], v[94:95], v[110:111], v[106:107] neg_lo:[0,0,1] neg_hi:[0,0,1]
	v_pk_fma_f32 v[112:113], v[92:93], v[108:109], v[104:105] neg_lo:[0,0,1] neg_hi:[0,0,1]
	s_waitcnt lgkmcnt(0)
	v_pk_mul_f32 v[92:93], v[102:103], v[130:131]
	v_pk_mul_f32 v[94:95], v[100:101], v[116:117]
	v_pk_fma_f32 v[122:123], v[90:91], v[98:99], v[92:93] neg_lo:[0,0,1] neg_hi:[0,0,1]
	v_pk_fma_f32 v[120:121], v[88:89], v[96:97], v[94:95] neg_lo:[0,0,1] neg_hi:[0,0,1]

; DI unsigned pk2(float lo, float hi) { f32x2 v = {lo, hi}; bf16x2_t b = __builtin_convertvector(v, bf16x2_t); return __builtin_bit_cast(unsigned, b); }
; template <int MODE> DI void epilogue(const Epi& E, f32x4 (&acc)[2][2][4][2], const Unit& u, int wr, int wc, int fr, int fq) {
;     ...
;                 const int row = row0 + ai * HALF + m * 16; const int pos = pos_of_row(row);
;                 f32x4 c0 = {1.f, 1.f, 1.f, 1.f}, c1 = c0, s0 = {0.f, 0.f, 0.f, 0.f}, s1 = s0;
;                 if (rp) { const f32x4* rt = (const f32x4*)(E.rope + (size_t)pos * 16); c0 = rt[0]; c1 = rt[1]; s0 = rt[2]; s1 = rt[3]; }
;                 const int pl0 = ((colt / 1536) * 3 + typ) * 8;
; #pragma unroll
;                 for (int bj = 0; bj < 2; ++bj) {
;                     const int hh_ = (((colt & 511) + wc * 64) >> 6);
;                     bf16_t* rowp = E.O + ((size_t)(pl0 + hh_) * T + row) * 64 + bj * 32 + 8 * fq;
;                     f32x4 v0 = acc[ai][bj][m][0], v1 = acc[ai][bj][m][1];
;                     if (rp && bj == 0) {
;                         f32x4 p0, p1;
; #pragma unroll
;                         for (int e = 0; e < 4; ++e) { p0[e] = __shfl_xor(v0[e], 16); p1[e] = __shfl_xor(v1[e], 16); }
;                         if (fq == 0) { v0 = v0 * c0 - p0 * s0; v1 = v1 * c1 - p1 * s1; }
;                         else if (fq == 1) { v0 = v0 * c0 + p0 * s0; v1 = v1 * c1 + p1 * s1; }
;                     }
;                     u32x4 w; w.x = pk2(v0[0], v0[1]); w.y = pk2(v0[2], v0[3]); w.z = pk2(v1[0], v1[1]); w.w = pk2(v1[2], v1[3]);
;                     __builtin_nontemporal_store(w, (u32x4*)rowp);
.LBB0_239:
	v_ashrrev_i32_e32 v129, 31, v128
	s_waitcnt vmcnt(2)
	v_lshl_add_u64 v[96:97], s[20:21], 0, v[128:129]
	v_lshlrev_b64 v[96:97], 7, v[96:97]
	v_lshl_add_u64 v[96:97], v[168:169], 0, v[96:97]
	v_cvt_pk_bf16_f32 v92, v92, v93
	v_cvt_pk_bf16_f32 v93, v94, v95
	v_cvt_pk_bf16_f32 v94, v88, v89
	v_cvt_pk_bf16_f32 v95, v90, v91
	v_cvt_pk_bf16_f32 v84, v84, v85
	v_cvt_pk_bf16_f32 v85, v86, v87
	v_cvt_pk_bf16_f32 v86, v80, v81
	v_cvt_pk_bf16_f32 v87, v82, v83
	v_or_b32_e32 v220, 48, v178
	s_and_b64 vcc, exec, s[4:5]
	s_cbranch_vccnz .Lrope_pf_skip_3
	v_cmp_gt_i32_e32 vcc, s36, v220
	s_nop 1
	v_cndmask_b32_e32 v221, v200, v201, vcc
	v_and_b32_e32 v221, v221, v220
	v_lshlrev_b32_e32 v221, 6, v221
	global_load_dwordx4 v[204:207], v221, s[6:7] offset:32
	global_load_dwordx4 v[208:211], v221, s[6:7] offset:48
	global_load_dwordx4 v[212:215], v221, s[6:7] offset:16
	global_load_dwordx4 v[216:219], v221, s[6:7]
.Lrope_pf_skip_3:
	s_and_b64 vcc, exec, s[4:5]
	v_or_b32_e32 v112, 48, v178
	global_store_dwordx4 v[96:97], v[92:95], off nt
	global_store_dwordx4 v[96:97], v[84:87], off offset:64 nt
	s_cbranch_vccnz .LBB0_241
	v_cmp_gt_i32_e32 vcc, s36, v112
	s_nop 1
	v_cndmask_b32_e32 v80, v200, v201, vcc
	v_and_b32_e32 v80, v80, v112
	v_lshlrev_b32_e32 v92, 6, v80
	s_waitcnt vmcnt(2)
	v_mov_b32_e32 v88, v204
	v_mov_b32_e32 v89, v205
	v_mov_b32_e32 v90, v206
	v_mov_b32_e32 v91, v207
	v_mov_b32_e32 v84, v208
	v_mov_b32_e32 v85, v209
	v_mov_b32_e32 v86, v210
	v_mov_b32_e32 v87, v211
	v_mov_b32_e32 v80, v212
	v_mov_b32_e32 v81, v213
	v_mov_b32_e32 v82, v214
	v_mov_b32_e32 v83, v215
	v_mov_b32_e32 v92, v216
	v_mov_b32_e32 v93, v217
	v_mov_b32_e32 v94, v218
	v_mov_b32_e32 v95, v219
	s_and_b64 vcc, exec, s[4:5]
	s_cbranch_vccz .LBB0_242
	s_branch .LBB0_249

; template <int MODE> DI void epilogue(const Epi& E, f32x4 (&acc)[2][2][4][2], const Unit& u, int wr, int wc, int fr, int fq) {
;     ...
;                     if (rp && bj == 0) {
;                         f32x4 p0, p1;
; #pragma unroll
;                         for (int e = 0; e < 4; ++e) { p0[e] = __shfl_xor(v0[e], 16); p1[e] = __shfl_xor(v1[e], 16); }
;                         if (fq == 0) { v0 = v0 * c0 - p0 * s0; v1 = v1 * c1 - p1 * s1; }
;                         else if (fq == 1) { v0 = v0 * c0 + p0 * s0; v1 = v1 * c1 + p1 * s1; }
.LBB0_242:
	v_and_b32_e32 v97, 64, v194
	v_xor_b32_e32 v96, 16, v194
	v_add_u32_e32 v97, 64, v97
	v_cmp_lt_i32_e32 vcc, v96, v97
	s_nop 1
	v_cndmask_b32_e32 v96, v194, v96, vcc
	v_lshlrev_b32_e32 v96, 2, v96
	s_waitcnt vmcnt(2)
	ds_bpermute_b32 v108, v96, v76
	ds_bpermute_b32 v100, v96, v72
	ds_bpermute_b32 v109, v96, v77
	ds_bpermute_b32 v101, v96, v73
	s_waitcnt lgkmcnt(10)
	ds_bpermute_b32 v116, v96, v78
	ds_bpermute_b32 v114, v96, v74
	s_waitcnt lgkmcnt(10)
	ds_bpermute_b32 v117, v96, v79
	ds_bpermute_b32 v115, v96, v75
	v_cmp_lt_i32_e32 vcc, 0, v184
	s_and_saveexec_b64 s[22:23], vcc
	s_xor_b64 s[22:23], exec, s[22:23]
	s_cbranch_execz .LBB0_246
	v_mov_b64_e32 v[106:107], v[74:75]
	v_mov_b64_e32 v[98:99], v[78:79]
	v_cmp_eq_u32_e32 vcc, 1, v184
	v_mov_b64_e32 v[104:105], v[72:73]
	v_mov_b64_e32 v[96:97], v[76:77]
	s_and_saveexec_b64 s[24:25], vcc
	s_cbranch_execz .LBB0_245
	s_waitcnt lgkmcnt(1)
	v_pk_mul_f32 v[90:91], v[90:91], v[116:117]
	v_pk_mul_f32 v[88:89], v[88:89], v[108:109]
	s_waitcnt lgkmcnt(0)
	v_pk_mul_f32 v[86:87], v[86:87], v[114:115]
	v_pk_mul_f32 v[84:85], v[84:85], v[100:101]
	s_waitcnt vmcnt(2)
	v_pk_fma_f32 v[98:99], v[78:79], v[94:95], v[90:91]
	v_pk_fma_f32 v[96:97], v[76:77], v[92:93], v[88:89]
	v_pk_fma_f32 v[106:107], v[74:75], v[82:83], v[86:87]
	v_pk_fma_f32 v[104:105], v[72:73], v[80:81], v[84:85]

; template <int MODE> DI void epilogue(const Epi& E, f32x4 (&acc)[2][2][4][2], const Unit& u, int wr, int wc, int fr, int fq) {
;     ...
;                     if (rp && bj == 0) {
;                         f32x4 p0, p1;
; #pragma unroll
;                         for (int e = 0; e < 4; ++e) { p0[e] = __shfl_xor(v0[e], 16); p1[e] = __shfl_xor(v1[e], 16); }
;                         if (fq == 0) { v0 = v0 * c0 - p0 * s0; v1 = v1 * c1 - p1 * s1; }
;                         else if (fq == 1) { v0 = v0 * c0 + p0 * s0; v1 = v1 * c1 + p1 * s1; }
.LBB0_246:
	s_andn2_saveexec_b64 s[22:23], s[22:23]
	s_cbranch_execz .LBB0_248
	s_waitcnt lgkmcnt(1)
	v_pk_mul_f32 v[90:91], v[90:91], v[116:117]
	v_pk_mul_f32 v[88:89], v[88:89], v[108:109]
	s_waitcnt vmcnt(2)
	v_pk_fma_f32 v[98:99], v[78:79], v[94:95], v[90:91] neg_lo:[0,0,1] neg_hi:[0,0,1]
	v_pk_fma_f32 v[96:97], v[76:77], v[92:93], v[88:89] neg_lo:[0,0,1] neg_hi:[0,0,1]
	s_waitcnt lgkmcnt(0)
	v_pk_mul_f32 v[76:77], v[86:87], v[114:115]
	v_pk_mul_f32 v[78:79], v[84:85], v[100:101]
	v_pk_fma_f32 v[106:107], v[74:75], v[82:83], v[76:77] neg_lo:[0,0,1] neg_hi:[0,0,1]
	v_pk_fma_f32 v[104:105], v[72:73], v[80:81], v[78:79] neg_lo:[0,0,1] neg_hi:[0,0,1]

; DI unsigned pk2(float lo, float hi) { f32x2 v = {lo, hi}; bf16x2_t b = __builtin_convertvector(v, bf16x2_t); return __builtin_bit_cast(unsigned, b); }
; template <int MODE> DI void epilogue(const Epi& E, f32x4 (&acc)[2][2][4][2], const Unit& u, int wr, int wc, int fr, int fq) {
;     ...
;                 const int row = row0 + ai * HALF + m * 16; const int pos = pos_of_row(row);
;                 f32x4 c0 = {1.f, 1.f, 1.f, 1.f}, c1 = c0, s0 = {0.f, 0.f, 0.f, 0.f}, s1 = s0;
;                 if (rp) { const f32x4* rt = (const f32x4*)(E.rope + (size_t)pos * 16); c0 = rt[0]; c1 = rt[1]; s0 = rt[2]; s1 = rt[3]; }
;                 const int pl0 = ((colt / 1536) * 3 + typ) * 8;
; #pragma unroll
;                 for (int bj = 0; bj < 2; ++bj) {
;                     const int hh_ = (((colt & 511) + wc * 64) >> 6);
;                     bf16_t* rowp = E.O + ((size_t)(pl0 + hh_) * T + row) * 64 + bj * 32 + 8 * fq;
;                     f32x4 v0 = acc[ai][bj][m][0], v1 = acc[ai][bj][m][1];
;                     if (rp && bj == 0) {
;                         f32x4 p0, p1;
; #pragma unroll
;                         for (int e = 0; e < 4; ++e) { p0[e] = __shfl_xor(v0[e], 16); p1[e] = __shfl_xor(v1[e], 16); }
;                         if (fq == 0) { v0 = v0 * c0 - p0 * s0; v1 = v1 * c1 - p1 * s1; }
;                         else if (fq == 1) { v0 = v0 * c0 + p0 * s0; v1 = v1 * c1 + p1 * s1; }
;                     }
;                     u32x4 w; w.x = pk2(v0[0], v0[1]); w.y = pk2(v0[2], v0[3]); w.z = pk2(v1[0], v1[1]); w.w = pk2(v1[2], v1[3]);
;                     __builtin_nontemporal_store(w, (u32x4*)rowp);
.LBB0_249:
	v_ashrrev_i32_e32 v113, 31, v112
	s_waitcnt vmcnt(2)
	v_lshl_add_u64 v[80:81], s[20:21], 0, v[112:113]
	v_lshlrev_b64 v[80:81], 7, v[80:81]
	v_lshl_add_u64 v[80:81], v[168:169], 0, v[80:81]
	v_cvt_pk_bf16_f32 v76, v76, v77
	v_cvt_pk_bf16_f32 v77, v78, v79
	v_cvt_pk_bf16_f32 v78, v72, v73
	v_cvt_pk_bf16_f32 v79, v74, v75
	v_cvt_pk_bf16_f32 v68, v68, v69
	v_cvt_pk_bf16_f32 v69, v70, v71
	v_cvt_pk_bf16_f32 v70, v64, v65
	v_cvt_pk_bf16_f32 v71, v66, v67
	v_add_u32_e32 v220, 0x80, v178
	s_and_b64 vcc, exec, s[4:5]
	s_cbranch_vccnz .Lrope_pf_skip_4
	v_cmp_gt_i32_e32 vcc, s43, v178
	s_nop 1
	v_cndmask_b32_e32 v221, v192, v193, vcc
	v_and_b32_e32 v221, v221, v220
	v_lshlrev_b32_e32 v221, 6, v221
	global_load_dwordx4 v[204:207], v221, s[6:7] offset:32
	global_load_dwordx4 v[208:211], v221, s[6:7] offset:48
	global_load_dwordx4 v[212:215], v221, s[6:7] offset:16
	global_load_dwordx4 v[216:219], v221, s[6:7]
.Lrope_pf_skip_4:
	s_and_b64 vcc, exec, s[4:5]
	v_add_u32_e32 v96, 0x80, v178
	global_store_dwordx4 v[80:81], v[76:79], off nt
	global_store_dwordx4 v[80:81], v[68:71], off offset:64 nt
	s_cbranch_vccnz .LBB0_251
	v_cmp_gt_i32_e32 vcc, s43, v178
	s_nop 1
	v_cndmask_b32_e32 v64, v192, v193, vcc
	v_and_b32_e32 v64, v64, v96
	v_lshlrev_b32_e32 v76, 6, v64
	s_waitcnt vmcnt(2)
	v_mov_b32_e32 v72, v204
	v_mov_b32_e32 v73, v205
	v_mov_b32_e32 v74, v206
	v_mov_b32_e32 v75, v207
	v_mov_b32_e32 v68, v208
	v_mov_b32_e32 v69, v209
	v_mov_b32_e32 v70, v210
	v_mov_b32_e32 v71, v211
	v_mov_b32_e32 v64, v212
	v_mov_b32_e32 v65, v213
	v_mov_b32_e32 v66, v214
	v_mov_b32_e32 v67, v215
	v_mov_b32_e32 v76, v216
	v_mov_b32_e32 v77, v217
	v_mov_b32_e32 v78, v218
	v_mov_b32_e32 v79, v219
	s_and_b64 vcc, exec, s[4:5]
	s_cbranch_vccz .LBB0_252
	s_branch .LBB0_259

; template <int MODE> DI void epilogue(const Epi& E, f32x4 (&acc)[2][2][4][2], const Unit& u, int wr, int wc, int fr, int fq) {
;     ...
;                     if (rp && bj == 0) {
;                         f32x4 p0, p1;
; #pragma unroll
;                         for (int e = 0; e < 4; ++e) { p0[e] = __shfl_xor(v0[e], 16); p1[e] = __shfl_xor(v1[e], 16); }
;                         if (fq == 0) { v0 = v0 * c0 - p0 * s0; v1 = v1 * c1 - p1 * s1; }
;                         else if (fq == 1) { v0 = v0 * c0 + p0 * s0; v1 = v1 * c1 + p1 * s1; }
.LBB0_252:
	v_and_b32_e32 v81, 64, v194
	v_xor_b32_e32 v80, 16, v194
	v_add_u32_e32 v81, 64, v81
	v_cmp_lt_i32_e32 vcc, v80, v81
	s_nop 1
	v_cndmask_b32_e32 v80, v194, v80, vcc
	v_lshlrev_b32_e32 v80, 2, v80
	s_waitcnt vmcnt(2)
	ds_bpermute_b32 v92, v80, v60
	ds_bpermute_b32 v84, v80, v56
	ds_bpermute_b32 v93, v80, v61
	ds_bpermute_b32 v85, v80, v57
	s_waitcnt lgkmcnt(10)
	ds_bpermute_b32 v100, v80, v62
	ds_bpermute_b32 v98, v80, v58
	s_waitcnt lgkmcnt(10)
	ds_bpermute_b32 v101, v80, v63
	ds_bpermute_b32 v99, v80, v59
	v_cmp_lt_i32_e32 vcc, 0, v184
	s_and_saveexec_b64 s[22:23], vcc
	s_xor_b64 s[22:23], exec, s[22:23]
	s_cbranch_execz .LBB0_256
	v_mov_b64_e32 v[90:91], v[58:59]
	v_mov_b64_e32 v[82:83], v[62:63]
	v_cmp_eq_u32_e32 vcc, 1, v184
	v_mov_b64_e32 v[88:89], v[56:57]
	v_mov_b64_e32 v[80:81], v[60:61]
	s_and_saveexec_b64 s[24:25], vcc
	s_cbranch_execz .LBB0_255
	s_waitcnt lgkmcnt(1)
	v_pk_mul_f32 v[74:75], v[74:75], v[100:101]
	v_pk_mul_f32 v[72:73], v[72:73], v[92:93]
	s_waitcnt lgkmcnt(0)
	v_pk_mul_f32 v[70:71], v[70:71], v[98:99]
	v_pk_mul_f32 v[68:69], v[68:69], v[84:85]
	s_waitcnt vmcnt(2)
	v_pk_fma_f32 v[82:83], v[62:63], v[78:79], v[74:75]
	v_pk_fma_f32 v[80:81], v[60:61], v[76:77], v[72:73]
	v_pk_fma_f32 v[90:91], v[58:59], v[66:67], v[70:71]
	v_pk_fma_f32 v[88:89], v[56:57], v[64:65], v[68:69]

; template <int MODE> DI void epilogue(const Epi& E, f32x4 (&acc)[2][2][4][2], const Unit& u, int wr, int wc, int fr, int fq) {
;     ...
;                     if (rp && bj == 0) {
;                         f32x4 p0, p1;
; #pragma unroll
;                         for (int e = 0; e < 4; ++e) { p0[e] = __shfl_xor(v0[e], 16); p1[e] = __shfl_xor(v1[e], 16); }
;                         if (fq == 0) { v0 = v0 * c0 - p0 * s0; v1 = v1 * c1 - p1 * s1; }
;                         else if (fq == 1) { v0 = v0 * c0 + p0 * s0; v1 = v1 * c1 + p1 * s1; }
.LBB0_256:
	s_andn2_saveexec_b64 s[22:23], s[22:23]
	s_cbranch_execz .LBB0_258
	s_waitcnt lgkmcnt(1)
	v_pk_mul_f32 v[74:75], v[74:75], v[100:101]
	v_pk_mul_f32 v[72:73], v[72:73], v[92:93]
	s_waitcnt vmcnt(2)
	v_pk_fma_f32 v[82:83], v[62:63], v[78:79], v[74:75] neg_lo:[0,0,1] neg_hi:[0,0,1]
	v_pk_fma_f32 v[80:81], v[60:61], v[76:77], v[72:73] neg_lo:[0,0,1] neg_hi:[0,0,1]
	s_waitcnt lgkmcnt(0)
	v_pk_mul_f32 v[60:61], v[70:71], v[98:99]
	v_pk_mul_f32 v[62:63], v[68:69], v[84:85]
	v_pk_fma_f32 v[90:91], v[58:59], v[66:67], v[60:61] neg_lo:[0,0,1] neg_hi:[0,0,1]
	v_pk_fma_f32 v[88:89], v[56:57], v[64:65], v[62:63] neg_lo:[0,0,1] neg_hi:[0,0,1]

; DI unsigned pk2(float lo, float hi) { f32x2 v = {lo, hi}; bf16x2_t b = __builtin_convertvector(v, bf16x2_t); return __builtin_bit_cast(unsigned, b); }
; template <int MODE> DI void epilogue(const Epi& E, f32x4 (&acc)[2][2][4][2], const Unit& u, int wr, int wc, int fr, int fq) {
;     ...
;                 const int row = row0 + ai * HALF + m * 16; const int pos = pos_of_row(row);
;                 f32x4 c0 = {1.f, 1.f, 1.f, 1.f}, c1 = c0, s0 = {0.f, 0.f, 0.f, 0.f}, s1 = s0;
;                 if (rp) { const f32x4* rt = (const f32x4*)(E.rope + (size_t)pos * 16); c0 = rt[0]; c1 = rt[1]; s0 = rt[2]; s1 = rt[3]; }
;                 const int pl0 = ((colt / 1536) * 3 + typ) * 8;
; #pragma unroll
;                 for (int bj = 0; bj < 2; ++bj) {
;                     const int hh_ = (((colt & 511) + wc * 64) >> 6);
;                     bf16_t* rowp = E.O + ((size_t)(pl0 + hh_) * T + row) * 64 + bj * 32 + 8 * fq;
;                     f32x4 v0 = acc[ai][bj][m][0], v1 = acc[ai][bj][m][1];
;                     if (rp && bj == 0) {
;                         f32x4 p0, p1;
; #pragma unroll
;                         for (int e = 0; e < 4; ++e) { p0[e] = __shfl_xor(v0[e], 16); p1[e] = __shfl_xor(v1[e], 16); }
;                         if (fq == 0) { v0 = v0 * c0 - p0 * s0; v1 = v1 * c1 - p1 * s1; }
;                         else if (fq == 1) { v0 = v0 * c0 + p0 * s0; v1 = v1 * c1 + p1 * s1; }
;                     }
;                     u32x4 w; w.x = pk2(v0[0], v0[1]); w.y = pk2(v0[2], v0[3]); w.z = pk2(v1[0], v1[1]); w.w = pk2(v1[2], v1[3]);
;                     __builtin_nontemporal_store(w, (u32x4*)rowp);
.LBB0_259:
	v_ashrrev_i32_e32 v97, 31, v96
	s_waitcnt vmcnt(2)
	v_lshl_add_u64 v[64:65], s[20:21], 0, v[96:97]
	v_lshlrev_b64 v[64:65], 7, v[64:65]
	v_lshl_add_u64 v[64:65], v[168:169], 0, v[64:65]
	v_cvt_pk_bf16_f32 v60, v60, v61
	v_cvt_pk_bf16_f32 v61, v62, v63
	v_cvt_pk_bf16_f32 v62, v56, v57
	v_cvt_pk_bf16_f32 v63, v58, v59
	v_cvt_pk_bf16_f32 v52, v52, v53
	v_cvt_pk_bf16_f32 v53, v54, v55
	v_cvt_pk_bf16_f32 v54, v48, v49
	v_cvt_pk_bf16_f32 v55, v50, v51
	v_add_u32_e32 v220, 0x90, v178
	s_and_b64 vcc, exec, s[4:5]
	s_cbranch_vccnz .Lrope_pf_skip_5
	v_cmp_gt_i32_e32 vcc, s44, v178
	s_nop 1
	v_cndmask_b32_e32 v221, v196, v197, vcc
	v_and_b32_e32 v221, v221, v220
	v_lshlrev_b32_e32 v221, 6, v221
	global_load_dwordx4 v[204:207], v221, s[6:7] offset:32
	global_load_dwordx4 v[208:211], v221, s[6:7] offset:48
	global_load_dwordx4 v[212:215], v221, s[6:7] offset:16
	global_load_dwordx4 v[216:219], v221, s[6:7]
.Lrope_pf_skip_5:
	s_and_b64 vcc, exec, s[4:5]
	v_add_u32_e32 v80, 0x90, v178
	global_store_dwordx4 v[64:65], v[60:63], off nt
	global_store_dwordx4 v[64:65], v[52:55], off offset:64 nt
	s_cbranch_vccnz .LBB0_261
	v_cmp_gt_i32_e32 vcc, s44, v178
	s_nop 1
	v_cndmask_b32_e32 v48, v196, v197, vcc
	v_and_b32_e32 v48, v48, v80
	v_lshlrev_b32_e32 v60, 6, v48
	s_waitcnt vmcnt(2)
	v_mov_b32_e32 v56, v204
	v_mov_b32_e32 v57, v205
	v_mov_b32_e32 v58, v206
	v_mov_b32_e32 v59, v207
	v_mov_b32_e32 v52, v208
	v_mov_b32_e32 v53, v209
	v_mov_b32_e32 v54, v210
	v_mov_b32_e32 v55, v211
	v_mov_b32_e32 v48, v212
	v_mov_b32_e32 v49, v213
	v_mov_b32_e32 v50, v214
	v_mov_b32_e32 v51, v215
	v_mov_b32_e32 v60, v216
	v_mov_b32_e32 v61, v217
	v_mov_b32_e32 v62, v218
	v_mov_b32_e32 v63, v219
	s_and_b64 vcc, exec, s[4:5]
	s_cbranch_vccz .LBB0_262
	s_branch .LBB0_269

; template <int MODE> DI void epilogue(const Epi& E, f32x4 (&acc)[2][2][4][2], const Unit& u, int wr, int wc, int fr, int fq) {
;     ...
;                     if (rp && bj == 0) {
;                         f32x4 p0, p1;
; #pragma unroll
;                         for (int e = 0; e < 4; ++e) { p0[e] = __shfl_xor(v0[e], 16); p1[e] = __shfl_xor(v1[e], 16); }
;                         if (fq == 0) { v0 = v0 * c0 - p0 * s0; v1 = v1 * c1 - p1 * s1; }
;                         else if (fq == 1) { v0 = v0 * c0 + p0 * s0; v1 = v1 * c1 + p1 * s1; }
.LBB0_262:
	v_and_b32_e32 v65, 64, v194
	v_xor_b32_e32 v64, 16, v194
	v_add_u32_e32 v65, 64, v65
	v_cmp_lt_i32_e32 vcc, v64, v65
	s_nop 1
	v_cndmask_b32_e32 v64, v194, v64, vcc
	v_lshlrev_b32_e32 v64, 2, v64
	s_waitcnt vmcnt(2)
	ds_bpermute_b32 v76, v64, v44
	ds_bpermute_b32 v68, v64, v40
	ds_bpermute_b32 v77, v64, v45
	ds_bpermute_b32 v69, v64, v41
	s_waitcnt lgkmcnt(10)
	ds_bpermute_b32 v84, v64, v46
	ds_bpermute_b32 v82, v64, v42
	s_waitcnt lgkmcnt(10)
	ds_bpermute_b32 v85, v64, v47
	ds_bpermute_b32 v83, v64, v43
	v_cmp_lt_i32_e32 vcc, 0, v184
	s_and_saveexec_b64 s[22:23], vcc
	s_xor_b64 s[22:23], exec, s[22:23]
	s_cbranch_execz .LBB0_266
	v_mov_b64_e32 v[74:75], v[42:43]
	v_mov_b64_e32 v[66:67], v[46:47]
	v_cmp_eq_u32_e32 vcc, 1, v184
	v_mov_b64_e32 v[72:73], v[40:41]
	v_mov_b64_e32 v[64:65], v[44:45]
	s_and_saveexec_b64 s[24:25], vcc
	s_cbranch_execz .LBB0_265
	s_waitcnt lgkmcnt(1)
	v_pk_mul_f32 v[58:59], v[58:59], v[84:85]
	v_pk_mul_f32 v[56:57], v[56:57], v[76:77]
	s_waitcnt lgkmcnt(0)
	v_pk_mul_f32 v[54:55], v[54:55], v[82:83]
	v_pk_mul_f32 v[52:53], v[52:53], v[68:69]
	s_waitcnt vmcnt(2)
	v_pk_fma_f32 v[66:67], v[46:47], v[62:63], v[58:59]
	v_pk_fma_f32 v[64:65], v[44:45], v[60:61], v[56:57]
	v_pk_fma_f32 v[74:75], v[42:43], v[50:51], v[54:55]
	v_pk_fma_f32 v[72:73], v[40:41], v[48:49], v[52:53]

; template <int MODE> DI void epilogue(const Epi& E, f32x4 (&acc)[2][2][4][2], const Unit& u, int wr, int wc, int fr, int fq) {
;     ...
;                     if (rp && bj == 0) {
;                         f32x4 p0, p1;
; #pragma unroll
;                         for (int e = 0; e < 4; ++e) { p0[e] = __shfl_xor(v0[e], 16); p1[e] = __shfl_xor(v1[e], 16); }
;                         if (fq == 0) { v0 = v0 * c0 - p0 * s0; v1 = v1 * c1 - p1 * s1; }
;                         else if (fq == 1) { v0 = v0 * c0 + p0 * s0; v1 = v1 * c1 + p1 * s1; }
.LBB0_266:
	s_andn2_saveexec_b64 s[22:23], s[22:23]
	s_cbranch_execz .LBB0_268
	s_waitcnt lgkmcnt(1)
	v_pk_mul_f32 v[58:59], v[58:59], v[84:85]
	v_pk_mul_f32 v[56:57], v[56:57], v[76:77]
	s_waitcnt vmcnt(2)
	v_pk_fma_f32 v[66:67], v[46:47], v[62:63], v[58:59] neg_lo:[0,0,1] neg_hi:[0,0,1]
	v_pk_fma_f32 v[64:65], v[44:45], v[60:61], v[56:57] neg_lo:[0,0,1] neg_hi:[0,0,1]
	s_waitcnt lgkmcnt(0)
	v_pk_mul_f32 v[44:45], v[54:55], v[82:83]
	v_pk_mul_f32 v[46:47], v[52:53], v[68:69]
	v_pk_fma_f32 v[74:75], v[42:43], v[50:51], v[44:45] neg_lo:[0,0,1] neg_hi:[0,0,1]
	v_pk_fma_f32 v[72:73], v[40:41], v[48:49], v[46:47] neg_lo:[0,0,1] neg_hi:[0,0,1]

; DI unsigned pk2(float lo, float hi) { f32x2 v = {lo, hi}; bf16x2_t b = __builtin_convertvector(v, bf16x2_t); return __builtin_bit_cast(unsigned, b); }
; template <int MODE> DI void epilogue(const Epi& E, f32x4 (&acc)[2][2][4][2], const Unit& u, int wr, int wc, int fr, int fq) {
;     ...
;                 const int row = row0 + ai * HALF + m * 16; const int pos = pos_of_row(row);
;                 f32x4 c0 = {1.f, 1.f, 1.f, 1.f}, c1 = c0, s0 = {0.f, 0.f, 0.f, 0.f}, s1 = s0;
;                 if (rp) { const f32x4* rt = (const f32x4*)(E.rope + (size_t)pos * 16); c0 = rt[0]; c1 = rt[1]; s0 = rt[2]; s1 = rt[3]; }
;                 const int pl0 = ((colt / 1536) * 3 + typ) * 8;
; #pragma unroll
;                 for (int bj = 0; bj < 2; ++bj) {
;                     const int hh_ = (((colt & 511) + wc * 64) >> 6);
;                     bf16_t* rowp = E.O + ((size_t)(pl0 + hh_) * T + row) * 64 + bj * 32 + 8 * fq;
;                     f32x4 v0 = acc[ai][bj][m][0], v1 = acc[ai][bj][m][1];
;                     if (rp && bj == 0) {
;                         f32x4 p0, p1;
; #pragma unroll
;                         for (int e = 0; e < 4; ++e) { p0[e] = __shfl_xor(v0[e], 16); p1[e] = __shfl_xor(v1[e], 16); }
;                         if (fq == 0) { v0 = v0 * c0 - p0 * s0; v1 = v1 * c1 - p1 * s1; }
;                         else if (fq == 1) { v0 = v0 * c0 + p0 * s0; v1 = v1 * c1 + p1 * s1; }
;                     }
;                     u32x4 w; w.x = pk2(v0[0], v0[1]); w.y = pk2(v0[2], v0[3]); w.z = pk2(v1[0], v1[1]); w.w = pk2(v1[2], v1[3]);
;                     __builtin_nontemporal_store(w, (u32x4*)rowp);
.LBB0_269:
	v_ashrrev_i32_e32 v81, 31, v80
	s_waitcnt vmcnt(2)
	v_lshl_add_u64 v[48:49], s[20:21], 0, v[80:81]
	v_lshlrev_b64 v[48:49], 7, v[48:49]
	v_lshl_add_u64 v[48:49], v[168:169], 0, v[48:49]
	v_cvt_pk_bf16_f32 v44, v44, v45
	v_cvt_pk_bf16_f32 v45, v46, v47
	v_cvt_pk_bf16_f32 v46, v40, v41
	v_cvt_pk_bf16_f32 v47, v42, v43
	v_cvt_pk_bf16_f32 v36, v36, v37
	v_cvt_pk_bf16_f32 v37, v38, v39
	v_cvt_pk_bf16_f32 v38, v32, v33
	v_cvt_pk_bf16_f32 v39, v34, v35
	v_add_u32_e32 v220, 0xa0, v178
	s_and_b64 vcc, exec, s[4:5]
	s_cbranch_vccnz .Lrope_pf_skip_6
	v_cmp_gt_i32_e32 vcc, s45, v178
	s_nop 1
	v_cndmask_b32_e32 v221, v198, v199, vcc
	v_and_b32_e32 v221, v221, v220
	v_lshlrev_b32_e32 v221, 6, v221
	global_load_dwordx4 v[204:207], v221, s[6:7] offset:32
	global_load_dwordx4 v[208:211], v221, s[6:7] offset:48
	global_load_dwordx4 v[212:215], v221, s[6:7] offset:16
	global_load_dwordx4 v[216:219], v221, s[6:7]
.Lrope_pf_skip_6:
	s_and_b64 vcc, exec, s[4:5]
	v_add_u32_e32 v64, 0xa0, v178
	global_store_dwordx4 v[48:49], v[44:47], off nt
	global_store_dwordx4 v[48:49], v[36:39], off offset:64 nt
	s_cbranch_vccnz .LBB0_271
	v_cmp_gt_i32_e32 vcc, s45, v178
	s_nop 1
	v_cndmask_b32_e32 v32, v198, v199, vcc
	v_and_b32_e32 v32, v32, v64
	v_lshlrev_b32_e32 v44, 6, v32
	s_waitcnt vmcnt(2)
	v_mov_b32_e32 v40, v204
	v_mov_b32_e32 v41, v205
	v_mov_b32_e32 v42, v206
	v_mov_b32_e32 v43, v207
	v_mov_b32_e32 v36, v208
	v_mov_b32_e32 v37, v209
	v_mov_b32_e32 v38, v210
	v_mov_b32_e32 v39, v211
	v_mov_b32_e32 v32, v212
	v_mov_b32_e32 v33, v213
	v_mov_b32_e32 v34, v214
	v_mov_b32_e32 v35, v215
	v_mov_b32_e32 v44, v216
	v_mov_b32_e32 v45, v217
	v_mov_b32_e32 v46, v218
	v_mov_b32_e32 v47, v219
	s_and_b64 vcc, exec, s[4:5]
	s_cbranch_vccz .LBB0_272
	s_branch .LBB0_279

; template <int MODE> DI void epilogue(const Epi& E, f32x4 (&acc)[2][2][4][2], const Unit& u, int wr, int wc, int fr, int fq) {
;     ...
;                     if (rp && bj == 0) {
;                         f32x4 p0, p1;
; #pragma unroll
;                         for (int e = 0; e < 4; ++e) { p0[e] = __shfl_xor(v0[e], 16); p1[e] = __shfl_xor(v1[e], 16); }
;                         if (fq == 0) { v0 = v0 * c0 - p0 * s0; v1 = v1 * c1 - p1 * s1; }
;                         else if (fq == 1) { v0 = v0 * c0 + p0 * s0; v1 = v1 * c1 + p1 * s1; }
.LBB0_272:
	v_and_b32_e32 v49, 64, v194
	v_xor_b32_e32 v48, 16, v194
	v_add_u32_e32 v49, 64, v49
	v_cmp_lt_i32_e32 vcc, v48, v49
	s_nop 1
	v_cndmask_b32_e32 v48, v194, v48, vcc
	v_lshlrev_b32_e32 v48, 2, v48
	s_waitcnt vmcnt(2)
	ds_bpermute_b32 v60, v48, v28
	ds_bpermute_b32 v52, v48, v24
	ds_bpermute_b32 v61, v48, v29
	ds_bpermute_b32 v53, v48, v25
	s_waitcnt lgkmcnt(10)
	ds_bpermute_b32 v68, v48, v30
	ds_bpermute_b32 v66, v48, v26
	s_waitcnt lgkmcnt(10)
	ds_bpermute_b32 v69, v48, v31
	ds_bpermute_b32 v67, v48, v27
	v_cmp_lt_i32_e32 vcc, 0, v184
	s_and_saveexec_b64 s[22:23], vcc
	s_xor_b64 s[22:23], exec, s[22:23]
	s_cbranch_execz .LBB0_276
	v_mov_b64_e32 v[58:59], v[26:27]
	v_mov_b64_e32 v[50:51], v[30:31]
	v_cmp_eq_u32_e32 vcc, 1, v184
	v_mov_b64_e32 v[56:57], v[24:25]
	v_mov_b64_e32 v[48:49], v[28:29]
	s_and_saveexec_b64 s[24:25], vcc
	s_cbranch_execz .LBB0_275
	s_waitcnt lgkmcnt(1)
	v_pk_mul_f32 v[42:43], v[42:43], v[68:69]
	v_pk_mul_f32 v[40:41], v[40:41], v[60:61]
	s_waitcnt lgkmcnt(0)
	v_pk_mul_f32 v[38:39], v[38:39], v[66:67]
	v_pk_mul_f32 v[36:37], v[36:37], v[52:53]
	s_waitcnt vmcnt(2)
	v_pk_fma_f32 v[50:51], v[30:31], v[46:47], v[42:43]
	v_pk_fma_f32 v[48:49], v[28:29], v[44:45], v[40:41]
	v_pk_fma_f32 v[58:59], v[26:27], v[34:35], v[38:39]
	v_pk_fma_f32 v[56:57], v[24:25], v[32:33], v[36:37]

; template <int MODE> DI void epilogue(const Epi& E, f32x4 (&acc)[2][2][4][2], const Unit& u, int wr, int wc, int fr, int fq) {
;     ...
;                     if (rp && bj == 0) {
;                         f32x4 p0, p1;
; #pragma unroll
;                         for (int e = 0; e < 4; ++e) { p0[e] = __shfl_xor(v0[e], 16); p1[e] = __shfl_xor(v1[e], 16); }
;                         if (fq == 0) { v0 = v0 * c0 - p0 * s0; v1 = v1 * c1 - p1 * s1; }
;                         else if (fq == 1) { v0 = v0 * c0 + p0 * s0; v1 = v1 * c1 + p1 * s1; }
.LBB0_276:
	s_andn2_saveexec_b64 s[22:23], s[22:23]
	s_cbranch_execz .LBB0_278
	s_waitcnt lgkmcnt(1)
	v_pk_mul_f32 v[42:43], v[42:43], v[68:69]
	v_pk_mul_f32 v[40:41], v[40:41], v[60:61]
	s_waitcnt vmcnt(2)
	v_pk_fma_f32 v[50:51], v[30:31], v[46:47], v[42:43] neg_lo:[0,0,1] neg_hi:[0,0,1]
	v_pk_fma_f32 v[48:49], v[28:29], v[44:45], v[40:41] neg_lo:[0,0,1] neg_hi:[0,0,1]
	s_waitcnt lgkmcnt(0)
	v_pk_mul_f32 v[28:29], v[38:39], v[66:67]
	v_pk_mul_f32 v[30:31], v[36:37], v[52:53]
	v_pk_fma_f32 v[58:59], v[26:27], v[34:35], v[28:29] neg_lo:[0,0,1] neg_hi:[0,0,1]
	v_pk_fma_f32 v[56:57], v[24:25], v[32:33], v[30:31] neg_lo:[0,0,1] neg_hi:[0,0,1]

; DI unsigned pk2(float lo, float hi) { f32x2 v = {lo, hi}; bf16x2_t b = __builtin_convertvector(v, bf16x2_t); return __builtin_bit_cast(unsigned, b); }
; template <int MODE> DI void epilogue(const Epi& E, f32x4 (&acc)[2][2][4][2], const Unit& u, int wr, int wc, int fr, int fq) {
;     ...
;                 const int row = row0 + ai * HALF + m * 16; const int pos = pos_of_row(row);
;                 f32x4 c0 = {1.f, 1.f, 1.f, 1.f}, c1 = c0, s0 = {0.f, 0.f, 0.f, 0.f}, s1 = s0;
;                 if (rp) { const f32x4* rt = (const f32x4*)(E.rope + (size_t)pos * 16); c0 = rt[0]; c1 = rt[1]; s0 = rt[2]; s1 = rt[3]; }
;                 const int pl0 = ((colt / 1536) * 3 + typ) * 8;
; #pragma unroll
;                 for (int bj = 0; bj < 2; ++bj) {
;                     const int hh_ = (((colt & 511) + wc * 64) >> 6);
;                     bf16_t* rowp = E.O + ((size_t)(pl0 + hh_) * T + row) * 64 + bj * 32 + 8 * fq;
;                     f32x4 v0 = acc[ai][bj][m][0], v1 = acc[ai][bj][m][1];
;                     if (rp && bj == 0) {
;                         f32x4 p0, p1;
; #pragma unroll
;                         for (int e = 0; e < 4; ++e) { p0[e] = __shfl_xor(v0[e], 16); p1[e] = __shfl_xor(v1[e], 16); }
;                         if (fq == 0) { v0 = v0 * c0 - p0 * s0; v1 = v1 * c1 - p1 * s1; }
;                         else if (fq == 1) { v0 = v0 * c0 + p0 * s0; v1 = v1 * c1 + p1 * s1; }
;                     }
;                     u32x4 w; w.x = pk2(v0[0], v0[1]); w.y = pk2(v0[2], v0[3]); w.z = pk2(v1[0], v1[1]); w.w = pk2(v1[2], v1[3]);
;                     __builtin_nontemporal_store(w, (u32x4*)rowp);
.LBB0_279:
	v_ashrrev_i32_e32 v65, 31, v64
	s_waitcnt vmcnt(2)
	v_lshl_add_u64 v[32:33], s[20:21], 0, v[64:65]
	v_lshlrev_b64 v[32:33], 7, v[32:33]
	v_lshl_add_u64 v[32:33], v[168:169], 0, v[32:33]
	v_cvt_pk_bf16_f32 v28, v28, v29
	v_cvt_pk_bf16_f32 v29, v30, v31
	v_cvt_pk_bf16_f32 v30, v24, v25
	v_cvt_pk_bf16_f32 v31, v26, v27
	v_cvt_pk_bf16_f32 v20, v20, v21
	v_cvt_pk_bf16_f32 v21, v22, v23
	v_cvt_pk_bf16_f32 v22, v16, v17
	v_cvt_pk_bf16_f32 v23, v18, v19
	s_and_b64 vcc, exec, s[4:5]
	s_waitcnt vmcnt(2)
	v_add_u32_e32 v44, 0xb0, v178
	global_store_dwordx4 v[32:33], v[28:31], off nt
	global_store_dwordx4 v[32:33], v[20:23], off offset:64 nt
	s_cbranch_vccnz .LBB0_287
	v_and_b32_e32 v17, 64, v194
	v_xor_b32_e32 v16, 16, v194
	v_add_u32_e32 v17, 64, v17
	v_cmp_lt_i32_e32 vcc, v16, v17
	s_nop 1
	v_cndmask_b32_e32 v16, v194, v16, vcc
	v_lshlrev_b32_e32 v18, 2, v16
	v_cmp_gt_i32_e32 vcc, s46, v178
	ds_bpermute_b32 v30, v18, v12
	ds_bpermute_b32 v16, v18, v8
	ds_bpermute_b32 v31, v18, v13
	ds_bpermute_b32 v17, v18, v9
	ds_bpermute_b32 v48, v18, v14
	ds_bpermute_b32 v46, v18, v10
	ds_bpermute_b32 v49, v18, v15
	ds_bpermute_b32 v47, v18, v11
	v_cndmask_b32_e32 v18, v200, v201, vcc
	v_and_b32_e32 v18, v18, v44
	v_lshlrev_b32_e32 v22, 6, v18
	global_load_dwordx4 v[26:29], v22, s[6:7] offset:48
	global_load_dwordx4 v[40:43], v22, s[6:7] offset:32
	global_load_dwordx4 v[18:21], v22, s[6:7] offset:16
	global_load_dwordx4 v[32:35], v22, s[6:7]
	v_cmp_lt_i32_e32 vcc, 0, v184
	s_and_saveexec_b64 s[4:5], vcc
	s_xor_b64 s[4:5], exec, s[4:5]
	s_cbranch_execz .LBB0_284
	v_mov_b64_e32 v[38:39], v[10:11]
	v_mov_b64_e32 v[24:25], v[14:15]
	v_cmp_eq_u32_e32 vcc, 1, v184
	v_mov_b64_e32 v[36:37], v[8:9]
	v_mov_b64_e32 v[22:23], v[12:13]
	s_and_saveexec_b64 s[22:23], vcc
	s_cbranch_execz .LBB0_283
	s_waitcnt vmcnt(2) lgkmcnt(1)
	v_pk_mul_f32 v[22:23], v[42:43], v[48:49]
	v_pk_mul_f32 v[30:31], v[40:41], v[30:31]
	s_waitcnt lgkmcnt(0)
	v_pk_mul_f32 v[28:29], v[28:29], v[46:47]
	v_pk_mul_f32 v[16:17], v[26:27], v[16:17]
	s_waitcnt vmcnt(0)
	v_pk_fma_f32 v[24:25], v[14:15], v[34:35], v[22:23]
	v_pk_fma_f32 v[22:23], v[12:13], v[32:33], v[30:31]
	v_pk_fma_f32 v[38:39], v[10:11], v[20:21], v[28:29]
	v_pk_fma_f32 v[36:37], v[8:9], v[18:19], v[16:17]
